# MODE 1 cross-attention unit epilogue: all 8 silu-gate loads issued up front (counted vmcnt) instead of one serialized load per iteration
# speedup vs baseline: 1.0209x; 1.0017x over previous
; __device__ __forceinline__ int crow(int r, int hi) { return (r & 3) + 8 * (r >> 2) + 4 * hi; }
; __device__ __forceinline__ void store_gated(const f32x16* v, float* stg, bf16_t* out, const bf16_t* gate, int lane, int r32, int hi, bool write) {
;     ...
;   for (int d0 = 0; d0 < 4; ++d0)
; #pragma unroll
;     for (int r = 0; r < 16; ++r) stg[crow(r, hi) * 128 + d0 * 32 + r32] = v[d0][r];
;   asm volatile("s_waitcnt lgkmcnt(0)" ::: "memory");
; #pragma unroll
;   for (int it = 0; it < 8; ++it) {
;     const int row = it * 4 + (lane >> 4), c8 = (lane & 15) * 8;
;     const f32x4 a = *(const f32x4*)(stg + row * 128 + c8), b = *(const f32x4*)(stg + row * 128 + c8 + 4);
;     const u32x4 g = *(const u32x4*)(gate + (long)row * INC + c8);
; template <int MODE, bool WRITE = true> ...
;     ...
;   if (hi == 0) li_l[r32] = l_reg; asm volatile("s_waitcnt lgkmcnt(0)" ::: "memory");
;   float rli[16];
; #pragma unroll
;   for (int r = 0; r < 16; ++r) rli[r] = __builtin_amdgcn_rcpf(li_l[crow(r, hi)]);
; #pragma unroll
;   for (int d0 = 0; d0 < 4; ++d0)
; #pragma unroll
;     for (int r = 0; r < 16; ++r) o[d0][r] *= rli[r];
.LBB0_379:
	s_or_b64 exec, exec, s[34:35]
	s_waitcnt lgkmcnt(0)
	v_lshl_add_u32 v72, v210, 4, s4
	ds_read_b128 v[64:67], v72
	ds_read_b128 v[68:71], v72 offset:32
	s_lshl_b32 s4, s49, 14
	s_add_i32 s6, s4, 0
	s_mul_hi_i32 s5, s76, 0x4800
	s_waitcnt lgkmcnt(1)
	v_rcp_f32_e32 v73, v64
	v_rcp_f32_e32 v74, v65
	v_rcp_f32_e32 v75, v66
	v_rcp_f32_e32 v76, v67
	ds_read_b128 v[64:67], v72 offset:64
	s_waitcnt lgkmcnt(1)
	v_rcp_f32_e32 v77, v68
	v_rcp_f32_e32 v78, v69
	v_rcp_f32_e32 v79, v70
	v_rcp_f32_e32 v80, v71
	ds_read_b128 v[68:71], v72 offset:96
	s_waitcnt lgkmcnt(1)
	v_rcp_f32_e32 v64, v64
	v_rcp_f32_e32 v65, v65
	v_rcp_f32_e32 v66, v66
	v_rcp_f32_e32 v67, v67
	s_waitcnt lgkmcnt(0)
	v_rcp_f32_e32 v68, v68
	v_rcp_f32_e32 v70, v70
	v_mul_f32_e32 v24, v24, v64
	v_mul_f32_e32 v25, v25, v65
	v_mul_f32_e32 v56, v56, v64
	v_mul_f32_e32 v57, v57, v65
	v_mul_f32_e32 v40, v40, v64
	v_mul_f32_e32 v41, v41, v65
	v_mul_f32_e32 v8, v8, v64
	v_mul_f32_e32 v9, v9, v65
	v_lshlrev_b32_e32 v64, 11, v210
	v_lshlrev_b32_e32 v65, 2, v209
	v_rcp_f32_e32 v69, v69
	v_rcp_f32_e32 v71, v71
	v_mul_f32_e32 v16, v16, v73
	v_mul_f32_e32 v48, v48, v73
	v_add3_u32 v64, s6, v64, v65
	v_mul_f32_e32 v17, v17, v74
	v_mul_f32_e32 v18, v18, v75
	v_mul_f32_e32 v49, v49, v74
	v_mul_f32_e32 v50, v50, v75
	s_barrier
	s_mulk_i32 s76, 0x4800
	ds_write2_b32 v64, v16, v48 offset1:32
	ds_write2_b32 v64, v17, v49 offset0:128 offset1:160
	v_add_u32_e32 v16, 0x400, v64
	v_mul_f32_e32 v19, v19, v76
	v_mul_f32_e32 v20, v20, v77
	v_mul_f32_e32 v21, v21, v78
	v_mul_f32_e32 v22, v22, v79
	v_mul_f32_e32 v51, v51, v76
	v_mul_f32_e32 v52, v52, v77
	v_mul_f32_e32 v54, v54, v79
	s_add_u32 s0, s0, s76
	ds_write2_b32 v16, v18, v50 offset1:32
	ds_write2_b32 v16, v19, v51 offset0:128 offset1:160
	v_add_u32_e32 v17, 0x1000, v64
	v_add_u32_e32 v18, 0x1400, v64
	v_mul_f32_e32 v23, v23, v80
	v_mul_f32_e32 v26, v26, v66
	v_mul_f32_e32 v28, v28, v68
	v_mul_f32_e32 v30, v30, v70
	v_mul_f32_e32 v53, v53, v78
	v_mul_f32_e32 v55, v55, v80
	v_mul_f32_e32 v58, v58, v66
	v_mul_f32_e32 v60, v60, v68
	v_mul_f32_e32 v62, v62, v70
	v_mul_f32_e32 v5, v5, v78
	s_addc_u32 s1, s1, s5
	ds_write2_b32 v17, v20, v52 offset1:32
	ds_write2_b32 v17, v21, v53 offset0:128 offset1:160
	ds_write2_b32 v18, v22, v54 offset1:32
	ds_write2_b32 v18, v23, v55 offset0:128 offset1:160
	v_add_u32_e32 v19, 0x2000, v64
	v_add_u32_e32 v20, 0x2400, v64
	v_add_u32_e32 v21, 0x3000, v64
	v_add_u32_e32 v22, 0x3400, v64
	v_mul_f32_e32 v27, v27, v67
	v_mul_f32_e32 v29, v29, v69
	v_mul_f32_e32 v31, v31, v71
	v_mul_f32_e32 v59, v59, v67
	v_mul_f32_e32 v61, v61, v69
	v_mul_f32_e32 v63, v63, v71
	v_mul_f32_e32 v32, v32, v73
	v_mul_f32_e32 v33, v33, v74
	v_mul_f32_e32 v34, v34, v75
	v_mul_f32_e32 v35, v35, v76
	v_mul_f32_e32 v36, v36, v77
	v_mul_f32_e32 v37, v37, v78
	v_mul_f32_e32 v38, v38, v79
	v_mul_f32_e32 v39, v39, v80
	v_mul_f32_e32 v42, v42, v66
	v_mul_f32_e32 v43, v43, v67
	v_mul_f32_e32 v44, v44, v68
	v_mul_f32_e32 v45, v45, v69
	v_mul_f32_e32 v46, v46, v70
	v_mul_f32_e32 v47, v47, v71
	v_mul_f32_e32 v0, v0, v73
	v_mul_f32_e32 v1, v1, v74
	v_mul_f32_e32 v2, v2, v75
	v_mul_f32_e32 v3, v3, v76
	v_mul_f32_e32 v4, v4, v77
	v_mul_f32_e32 v6, v6, v79
	v_mul_f32_e32 v7, v7, v80
	v_mul_f32_e32 v10, v10, v66
	v_mul_f32_e32 v11, v11, v67
	v_mul_f32_e32 v12, v12, v68
	v_mul_f32_e32 v13, v13, v69
	v_mul_f32_e32 v14, v14, v70
	v_mul_f32_e32 v15, v15, v71
	s_add_u32 s4, s22, s76
	ds_write2_b32 v19, v24, v56 offset1:32
	ds_write2_b32 v19, v25, v57 offset0:128 offset1:160
	ds_write2_b32 v20, v26, v58 offset1:32
	ds_write2_b32 v20, v27, v59 offset0:128 offset1:160
	ds_write2_b32 v21, v28, v60 offset1:32
	ds_write2_b32 v21, v29, v61 offset0:128 offset1:160
	ds_write2_b32 v22, v30, v62 offset1:32
	ds_write2_b32 v22, v31, v63 offset0:128 offset1:160
	ds_write2_b32 v64, v32, v0 offset0:64 offset1:96
	ds_write2_b32 v64, v33, v1 offset0:192 offset1:224
	ds_write2_b32 v16, v34, v2 offset0:64 offset1:96
	ds_write2_b32 v16, v35, v3 offset0:192 offset1:224
	ds_write2_b32 v17, v36, v4 offset0:64 offset1:96
	ds_write2_b32 v17, v37, v5 offset0:192 offset1:224
	ds_write2_b32 v18, v38, v6 offset0:64 offset1:96
	ds_write2_b32 v18, v39, v7 offset0:192 offset1:224
	ds_write2_b32 v19, v40, v8 offset0:64 offset1:96
	ds_write2_b32 v19, v41, v9 offset0:192 offset1:224
	ds_write2_b32 v20, v42, v10 offset0:64 offset1:96
	ds_write2_b32 v20, v43, v11 offset0:192 offset1:224
	ds_write2_b32 v21, v44, v12 offset0:64 offset1:96
	ds_write2_b32 v21, v45, v13 offset0:192 offset1:224
	ds_write2_b32 v22, v46, v14 offset0:64 offset1:96
	ds_write2_b32 v22, v47, v15 offset0:192 offset1:224
	v_and_b32_e32 v5, 0x78, v212
	s_addc_u32 s5, s48, s5
	v_lshrrev_b32_e32 v4, 4, v211
	v_lshlrev_b32_e32 v96, 1, v5
	v_lshl_add_u64 v[0:1], s[4:5], 0, v[96:97]
	s_mov_b64 s[4:5], 0x2c00
	v_mul_u32_u24_e32 v6, 0x2400, v4
	v_lshl_add_u64 v[2:3], v[0:1], 0, s[4:5]
	v_lshl_add_u64 v[0:1], s[0:1], 0, v[96:97]
	v_lshlrev_b32_e32 v96, 1, v6
	s_waitcnt lgkmcnt(0)
	v_lshl_add_u64 v[6:7], v[2:3], 0, v[96:97]
	v_mov_b32_e32 v182, v6
	v_mov_b32_e32 v183, v7
	s_mov_b32 s8, 0x12000
	s_mov_b32 s9, 0
	global_load_dwordx4 v[98:101], v[182:183], off
	v_lshl_add_u64 v[182:183], v[182:183], 0, s[8:9]
	global_load_dwordx4 v[102:105], v[182:183], off
	v_lshl_add_u64 v[182:183], v[182:183], 0, s[8:9]
	global_load_dwordx4 v[106:109], v[182:183], off
	v_lshl_add_u64 v[182:183], v[182:183], 0, s[8:9]
	global_load_dwordx4 v[110:113], v[182:183], off
	v_lshl_add_u64 v[182:183], v[182:183], 0, s[8:9]
	global_load_dwordx4 v[132:135], v[182:183], off
	v_lshl_add_u64 v[182:183], v[182:183], 0, s[8:9]
	global_load_dwordx4 v[136:139], v[182:183], off
	v_lshl_add_u64 v[182:183], v[182:183], 0, s[8:9]
	global_load_dwordx4 v[140:143], v[182:183], off
	v_lshl_add_u64 v[182:183], v[182:183], 0, s[8:9]
	global_load_dwordx4 v[186:189], v[182:183], off
	v_lshlrev_b32_e32 v5, 2, v5
	v_lshlrev_b32_e32 v4, 9, v4
	v_add3_u32 v8, s6, v5, v4
	ds_read_b128 v[14:17], v8
	ds_read_b128 v[18:21], v8 offset:16
	s_mov_b32 s0, 0x36000
	s_waitcnt vmcnt(7)
; __device__ __forceinline__ unsigned cvt_pk_bf16(float lo, float hi) { unsigned r; asm volatile("v_cvt_pk_bf16_f32 %0, %1, %2" : "=v"(r) : "v"(lo), "v"(hi)); return r; }
; __device__ __forceinline__ float bf_lo(unsigned u) { return __uint_as_float(u << 16); }
; __device__ __forceinline__ float bf_hi(unsigned u) { return __uint_as_float(u & 0xffff0000u); }
; __device__ __forceinline__ float sigmoidf_(float x) { return __builtin_amdgcn_rcpf(1.f + __expf(-x)); }
; __device__ __forceinline__ void store_gated(const f32x16* v, float* stg, bf16_t* out, const bf16_t* gate, int lane, int r32, int hi, bool write) {
;     ...
;   for (int it = 0; it < 8; ++it) {
;     const int row = it * 4 + (lane >> 4), c8 = (lane & 15) * 8;
;     const f32x4 a = *(const f32x4*)(stg + row * 128 + c8), b = *(const f32x4*)(stg + row * 128 + c8 + 4);
;     const u32x4 g = *(const u32x4*)(gate + (long)row * INC + c8);
;     float z[8] = {bf_lo(g.x), bf_hi(g.x), bf_lo(g.y), bf_hi(g.y), bf_lo(g.z), bf_hi(g.z), bf_lo(g.w), bf_hi(g.w)};
;     float y[8];
; #pragma unroll
;     for (int e = 0; e < 8; ++e) y[e] = (e < 4 ? a[e] : b[e - 4]) * z[e] * sigmoidf_(z[e]);
;     u32x4 w; w.x = cvt_pk_bf16(y[0], y[1]); w.y = cvt_pk_bf16(y[2], y[3]); w.z = cvt_pk_bf16(y[4], y[5]); w.w = cvt_pk_bf16(y[6], y[7]);
;     if (write) *(u32x4*)(out + (long)row * INC + c8) = w; else if (y[0] == 123.456f) out[0] = 0;
	v_mov_b32_e32 v10, v98
	v_mov_b32_e32 v11, v99
	v_mov_b32_e32 v12, v100
	v_mov_b32_e32 v13, v101
	v_lshlrev_b32_e32 v4, 16, v10
	v_and_b32_e32 v5, 0xffff0000, v10
	v_lshlrev_b32_e32 v9, 16, v11
	v_and_b32_e32 v10, 0xffff0000, v11
	v_mul_f32_e32 v23, 0xbfb8aa3b, v4
	v_mul_f32_e32 v24, 0xbfb8aa3b, v5
	s_waitcnt lgkmcnt(1)
	v_mul_f32_e32 v4, v14, v4
	v_mul_f32_e32 v5, v15, v5
	v_mul_f32_e32 v14, 0xbfb8aa3b, v9
	v_mul_f32_e32 v15, 0xbfb8aa3b, v10
	v_exp_f32_e32 v14, v14
	v_exp_f32_e32 v15, v15
	v_lshlrev_b32_e32 v11, 16, v12
	v_mul_f32_e32 v9, v16, v9
	v_add_f32_e32 v14, 1.0, v14
	v_add_f32_e32 v15, 1.0, v15
	v_mul_f32_e32 v16, 0xbfb8aa3b, v11
	v_rcp_f32_e32 v14, v14
	v_rcp_f32_e32 v15, v15
	v_exp_f32_e32 v16, v16
	v_and_b32_e32 v12, 0xffff0000, v12
	v_mul_f32_e32 v10, v17, v10
	v_mul_f32_e32 v9, v9, v14
	v_mul_f32_e32 v14, v10, v15
	v_add_f32_e32 v10, 1.0, v16
	v_mul_f32_e32 v15, 0xbfb8aa3b, v12
	v_rcp_f32_e32 v10, v10
	v_exp_f32_e32 v15, v15
	v_lshlrev_b32_e32 v22, 16, v13
	s_waitcnt lgkmcnt(0)
	v_mul_f32_e32 v11, v18, v11
	v_and_b32_e32 v13, 0xffff0000, v13
	v_mul_f32_e32 v16, v11, v10
	v_mul_f32_e32 v10, v19, v12
	v_add_f32_e32 v11, 1.0, v15
	v_mul_f32_e32 v12, 0xbfb8aa3b, v22
	v_exp_f32_e32 v23, v23
	v_rcp_f32_e32 v11, v11
	v_exp_f32_e32 v12, v12
	v_mul_f32_e32 v15, 0xbfb8aa3b, v13
	v_exp_f32_e32 v24, v24
	v_exp_f32_e32 v15, v15
	v_add_f32_e32 v23, 1.0, v23
	v_mul_f32_e32 v17, v10, v11
	v_add_f32_e32 v10, 1.0, v12
	v_rcp_f32_e32 v23, v23
	v_add_f32_e32 v24, 1.0, v24
	v_rcp_f32_e32 v10, v10
	v_add_f32_e32 v11, 1.0, v15
	v_rcp_f32_e32 v24, v24
	v_rcp_f32_e32 v11, v11
	v_mul_f32_e32 v12, v20, v22
	v_mul_f32_e32 v4, v4, v23
	v_mul_f32_e32 v15, v12, v10
	v_mul_f32_e32 v10, v21, v13
	v_mul_f32_e32 v5, v5, v24
	v_mul_f32_e32 v13, v10, v11
	v_cvt_pk_bf16_f32 v10, v4, v5
	v_add_co_u32_e32 v4, vcc, s90, v6
	v_cvt_pk_bf16_f32 v11, v9, v14
	v_cvt_pk_bf16_f32 v12, v16, v17
	v_cvt_pk_bf16_f32 v13, v15, v13
	s_nop 1
	v_addc_co_u32_e32 v5, vcc, 0, v7, vcc
	v_lshl_add_u64 v[4:5], v[0:1], 0, v[96:97]
	global_store_dwordx4 v[4:5], v[10:13], off
	ds_read_b128 v[10:13], v8 offset:2048
	ds_read_b128 v[18:21], v8 offset:2064
	s_waitcnt vmcnt(7)
	v_mov_b32_e32 v14, v102
	v_mov_b32_e32 v15, v103
	v_mov_b32_e32 v16, v104
	v_mov_b32_e32 v17, v105
	v_lshlrev_b32_e32 v9, 16, v14
	v_and_b32_e32 v14, 0xffff0000, v14
	v_lshlrev_b32_e32 v22, 16, v15
	v_and_b32_e32 v15, 0xffff0000, v15
	v_mul_f32_e32 v25, 0xbfb8aa3b, v9
	s_waitcnt lgkmcnt(1)
	v_mul_f32_e32 v9, v10, v9
	v_mul_f32_e32 v10, v11, v14
	v_mul_f32_e32 v11, 0xbfb8aa3b, v22
	v_mul_f32_e32 v26, 0xbfb8aa3b, v14
	v_exp_f32_e32 v11, v11
	v_mul_f32_e32 v14, 0xbfb8aa3b, v15
	v_exp_f32_e32 v14, v14
	v_lshlrev_b32_e32 v23, 16, v16
	v_add_f32_e32 v11, 1.0, v11
	v_mul_f32_e32 v12, v12, v22
	v_rcp_f32_e32 v11, v11
	v_add_f32_e32 v14, 1.0, v14
	v_mul_f32_e32 v22, 0xbfb8aa3b, v23
	v_rcp_f32_e32 v14, v14
	v_exp_f32_e32 v22, v22
	v_and_b32_e32 v16, 0xffff0000, v16
	v_mul_f32_e32 v11, v12, v11
	v_mul_f32_e32 v12, v13, v15
	v_mul_f32_e32 v12, v12, v14
	v_add_f32_e32 v13, 1.0, v22
	v_mul_f32_e32 v14, 0xbfb8aa3b, v16
	v_rcp_f32_e32 v13, v13
	v_exp_f32_e32 v14, v14
	v_lshlrev_b32_e32 v24, 16, v17
	s_waitcnt lgkmcnt(0)
	v_mul_f32_e32 v15, v18, v23
	v_exp_f32_e32 v26, v26
	v_and_b32_e32 v17, 0xffff0000, v17
	v_mul_f32_e32 v13, v15, v13
	v_mul_f32_e32 v15, v19, v16
	v_add_f32_e32 v14, 1.0, v14
	v_mul_f32_e32 v16, 0xbfb8aa3b, v24
	v_exp_f32_e32 v25, v25
	v_rcp_f32_e32 v14, v14
	v_exp_f32_e32 v16, v16
	v_mul_f32_e32 v18, 0xbfb8aa3b, v17
	v_exp_f32_e32 v18, v18
	v_add_f32_e32 v26, 1.0, v26
	v_add_f32_e32 v25, 1.0, v25
	v_rcp_f32_e32 v26, v26
	v_mul_f32_e32 v14, v15, v14
	v_add_f32_e32 v15, 1.0, v16
	v_rcp_f32_e32 v25, v25
	v_rcp_f32_e32 v15, v15
	v_add_f32_e32 v16, 1.0, v18
	v_rcp_f32_e32 v16, v16
	v_mul_f32_e32 v10, v10, v26
	v_mul_f32_e32 v18, v20, v24
	v_mul_f32_e32 v9, v9, v25
	v_mul_f32_e32 v15, v18, v15
	v_mul_f32_e32 v17, v21, v17
	v_cvt_pk_bf16_f32 v10, v9, v10
	v_cvt_pk_bf16_f32 v11, v11, v12
	v_cvt_pk_bf16_f32 v12, v13, v14
	v_add_co_u32_e32 v14, vcc, s21, v6
	v_mul_f32_e32 v16, v17, v16
	v_cvt_pk_bf16_f32 v13, v15, v16
	s_nop 0
	v_addc_co_u32_e32 v15, vcc, 0, v7, vcc
	v_add_co_u32_e32 v18, vcc, s90, v4
	s_waitcnt vmcnt(6)
	v_mov_b32_e32 v14, v106
	v_mov_b32_e32 v15, v107
	v_mov_b32_e32 v16, v108
	v_mov_b32_e32 v17, v109
	v_lshlrev_b32_e32 v9, 16, v14
	v_addc_co_u32_e32 v19, vcc, 0, v5, vcc
	global_store_dwordx4 v[18:19], v[10:13], off
	ds_read_b128 v[10:13], v8 offset:4096
	ds_read_b128 v[18:21], v8 offset:4112
	v_and_b32_e32 v14, 0xffff0000, v14
	v_lshlrev_b32_e32 v22, 16, v15
	v_and_b32_e32 v15, 0xffff0000, v15
	v_mul_f32_e32 v25, 0xbfb8aa3b, v9
	s_waitcnt lgkmcnt(1)
	v_mul_f32_e32 v9, v10, v9
	v_mul_f32_e32 v10, v11, v14
	v_mul_f32_e32 v11, 0xbfb8aa3b, v22
	v_mul_f32_e32 v26, 0xbfb8aa3b, v14
	v_exp_f32_e32 v11, v11
	v_mul_f32_e32 v14, 0xbfb8aa3b, v15
	v_exp_f32_e32 v14, v14
	v_lshlrev_b32_e32 v23, 16, v16
	v_add_f32_e32 v11, 1.0, v11
	v_mul_f32_e32 v12, v12, v22
	v_rcp_f32_e32 v11, v11
	v_add_f32_e32 v14, 1.0, v14
	v_mul_f32_e32 v22, 0xbfb8aa3b, v23
	v_rcp_f32_e32 v14, v14
	v_exp_f32_e32 v22, v22
	v_and_b32_e32 v16, 0xffff0000, v16
	v_mul_f32_e32 v11, v12, v11
	v_mul_f32_e32 v12, v13, v15
	v_mul_f32_e32 v12, v12, v14
	v_add_f32_e32 v13, 1.0, v22
	v_mul_f32_e32 v14, 0xbfb8aa3b, v16
	v_rcp_f32_e32 v13, v13
	v_exp_f32_e32 v14, v14
	v_lshlrev_b32_e32 v24, 16, v17
	v_and_b32_e32 v17, 0xffff0000, v17
	s_waitcnt lgkmcnt(0)
; __device__ __forceinline__ unsigned cvt_pk_bf16(float lo, float hi) { unsigned r; asm volatile("v_cvt_pk_bf16_f32 %0, %1, %2" : "=v"(r) : "v"(lo), "v"(hi)); return r; }
; __device__ __forceinline__ float bf_lo(unsigned u) { return __uint_as_float(u << 16); }
; __device__ __forceinline__ float bf_hi(unsigned u) { return __uint_as_float(u & 0xffff0000u); }
; __device__ __forceinline__ float sigmoidf_(float x) { return __builtin_amdgcn_rcpf(1.f + __expf(-x)); }
; __device__ __forceinline__ void store_gated(const f32x16* v, float* stg, bf16_t* out, const bf16_t* gate, int lane, int r32, int hi, bool write) {
;     ...
;   for (int it = 0; it < 8; ++it) {
;     const int row = it * 4 + (lane >> 4), c8 = (lane & 15) * 8;
;     const f32x4 a = *(const f32x4*)(stg + row * 128 + c8), b = *(const f32x4*)(stg + row * 128 + c8 + 4);
;     const u32x4 g = *(const u32x4*)(gate + (long)row * INC + c8);
;     float z[8] = {bf_lo(g.x), bf_hi(g.x), bf_lo(g.y), bf_hi(g.y), bf_lo(g.z), bf_hi(g.z), bf_lo(g.w), bf_hi(g.w)};
;     float y[8];
; #pragma unroll
;     for (int e = 0; e < 8; ++e) y[e] = (e < 4 ? a[e] : b[e - 4]) * z[e] * sigmoidf_(z[e]);
;     u32x4 w; w.x = cvt_pk_bf16(y[0], y[1]); w.y = cvt_pk_bf16(y[2], y[3]); w.z = cvt_pk_bf16(y[4], y[5]); w.w = cvt_pk_bf16(y[6], y[7]);
;     if (write) *(u32x4*)(out + (long)row * INC + c8) = w; else if (y[0] == 123.456f) out[0] = 0;
	v_mul_f32_e32 v15, v18, v23
	v_mul_f32_e32 v13, v15, v13
	v_mul_f32_e32 v15, v19, v16
	v_add_f32_e32 v14, 1.0, v14
	v_mul_f32_e32 v16, 0xbfb8aa3b, v24
	v_mul_f32_e32 v18, 0xbfb8aa3b, v17
	v_exp_f32_e32 v26, v26
	v_rcp_f32_e32 v14, v14
	v_exp_f32_e32 v16, v16
	v_exp_f32_e32 v18, v18
	v_exp_f32_e32 v25, v25
	v_add_f32_e32 v26, 1.0, v26
	v_mul_f32_e32 v14, v15, v14
	v_add_f32_e32 v15, 1.0, v16
	v_add_f32_e32 v16, 1.0, v18
	v_add_f32_e32 v25, 1.0, v25
	v_rcp_f32_e32 v26, v26
	v_rcp_f32_e32 v15, v15
	v_rcp_f32_e32 v16, v16
	v_rcp_f32_e32 v25, v25
	v_mul_f32_e32 v18, v20, v24
	v_mul_f32_e32 v17, v21, v17
	v_add_co_u32_e32 v6, vcc, s0, v6
	v_mul_f32_e32 v10, v10, v26
	v_mul_f32_e32 v15, v18, v15
	v_mul_f32_e32 v16, v17, v16
	v_addc_co_u32_e32 v7, vcc, 0, v7, vcc
	v_mul_f32_e32 v9, v9, v25
	v_cvt_pk_bf16_f32 v10, v9, v10
	v_cvt_pk_bf16_f32 v11, v11, v12
	v_cvt_pk_bf16_f32 v12, v13, v14
	v_cvt_pk_bf16_f32 v13, v15, v16
	v_add_co_u32_e32 v6, vcc, s21, v4
	ds_read_b128 v[18:21], v8 offset:6144
	ds_read_b128 v[22:25], v8 offset:6160
	v_addc_co_u32_e32 v7, vcc, 0, v5, vcc
	global_store_dwordx4 v[6:7], v[10:13], off
	s_waitcnt vmcnt(7)
	v_mov_b32_e32 v14, v110
	v_mov_b32_e32 v15, v111
	v_mov_b32_e32 v16, v112
	v_mov_b32_e32 v17, v113
	v_lshlrev_b32_e32 v6, 16, v14
	v_and_b32_e32 v7, 0xffff0000, v14
	v_lshlrev_b32_e32 v9, 16, v15
	v_and_b32_e32 v10, 0xffff0000, v15
	v_mul_f32_e32 v14, 0xbfb8aa3b, v6
	v_mul_f32_e32 v15, 0xbfb8aa3b, v7
	v_exp_f32_e32 v14, v14
	v_exp_f32_e32 v15, v15
	s_waitcnt lgkmcnt(1)
	v_mul_f32_e32 v6, v18, v6
	v_mul_f32_e32 v7, v19, v7
	v_add_f32_e32 v14, 1.0, v14
	v_add_f32_e32 v15, 1.0, v15
	v_rcp_f32_e32 v14, v14
	v_rcp_f32_e32 v15, v15
	v_lshlrev_b32_e32 v11, 16, v16
	v_and_b32_e32 v12, 0xffff0000, v16
	v_mul_f32_e32 v6, v6, v14
	v_mul_f32_e32 v7, v7, v15
	v_mul_f32_e32 v14, 0xbfb8aa3b, v9
	v_mul_f32_e32 v15, 0xbfb8aa3b, v10
	v_exp_f32_e32 v14, v14
	v_exp_f32_e32 v15, v15
	v_lshlrev_b32_e32 v13, 16, v17
	v_and_b32_e32 v16, 0xffff0000, v17
	v_add_f32_e32 v14, 1.0, v14
	v_add_f32_e32 v15, 1.0, v15
	v_mul_f32_e32 v17, 0xbfb8aa3b, v11
	v_rcp_f32_e32 v14, v14
	v_rcp_f32_e32 v15, v15
	v_exp_f32_e32 v17, v17
	v_mul_f32_e32 v9, v20, v9
	v_mul_f32_e32 v10, v21, v10
	v_mul_f32_e32 v9, v9, v14
	v_mul_f32_e32 v14, v10, v15
	v_add_f32_e32 v10, 1.0, v17
	v_mul_f32_e32 v15, 0xbfb8aa3b, v12
	v_rcp_f32_e32 v10, v10
	v_exp_f32_e32 v15, v15
	s_waitcnt lgkmcnt(0)
	v_mul_f32_e32 v11, v22, v11
	v_add_u32_e32 v22, 0x48000, v96
	v_mul_f32_e32 v17, v11, v10
	v_mul_f32_e32 v10, v23, v12
	v_add_f32_e32 v11, 1.0, v15
	v_mul_f32_e32 v12, 0xbfb8aa3b, v13
	v_rcp_f32_e32 v11, v11
	v_exp_f32_e32 v12, v12
	v_mul_f32_e32 v15, 0xbfb8aa3b, v16
	v_exp_f32_e32 v15, v15
	v_mul_f32_e32 v18, v10, v11
	v_add_f32_e32 v10, 1.0, v12
	v_rcp_f32_e32 v10, v10
	v_add_f32_e32 v11, 1.0, v15
	v_rcp_f32_e32 v11, v11
	v_mul_f32_e32 v12, v24, v13
	v_mul_f32_e32 v13, v12, v10
	v_mul_f32_e32 v10, v25, v16
	v_mov_b32_e32 v23, v97
	v_mul_f32_e32 v15, v10, v11
	v_cvt_pk_bf16_f32 v10, v6, v7
	v_lshl_add_u64 v[6:7], v[2:3], 0, v[22:23]
	v_cvt_pk_bf16_f32 v11, v9, v14
	v_cvt_pk_bf16_f32 v12, v17, v18
	v_cvt_pk_bf16_f32 v13, v13, v15
	v_add_co_u32_e32 v24, vcc, s0, v4
	v_lshl_add_u64 v[22:23], v[0:1], 0, v[22:23]
	s_nop 0
	v_addc_co_u32_e32 v25, vcc, 0, v5, vcc
	ds_read_b128 v[4:7], v8 offset:8192
	ds_read_b128 v[18:21], v8 offset:8208
	global_store_dwordx4 v[24:25], v[10:13], off
	v_add_u32_e32 v24, 0x5a000, v96
	v_mov_b32_e32 v25, v97
	s_mov_b64 s[0:1], 0
	s_waitcnt vmcnt(7)
	v_mov_b32_e32 v14, v132
	v_mov_b32_e32 v15, v133
	v_mov_b32_e32 v16, v134
	v_mov_b32_e32 v17, v135
	v_and_b32_e32 v10, 0xffff0000, v14
	s_waitcnt lgkmcnt(1)
	v_mul_f32_e32 v5, v5, v10
	v_mul_f32_e32 v10, 0xbfb8aa3b, v10
	v_exp_f32_e32 v10, v10
	v_lshlrev_b32_e32 v9, 16, v14
	v_and_b32_e32 v12, 0xffff0000, v15
	v_mul_f32_e32 v4, v4, v9
	v_mul_f32_e32 v9, 0xbfb8aa3b, v9
	v_lshlrev_b32_e32 v11, 16, v15
	v_mul_f32_e32 v7, v7, v12
	v_mul_f32_e32 v12, 0xbfb8aa3b, v12
	v_exp_f32_e32 v9, v9
	v_add_f32_e32 v10, 1.0, v10
	v_mul_f32_e32 v6, v6, v11
	v_mul_f32_e32 v11, 0xbfb8aa3b, v11
	v_exp_f32_e32 v12, v12
	v_rcp_f32_e32 v10, v10
	v_exp_f32_e32 v11, v11
	v_lshlrev_b32_e32 v13, 16, v16
	v_and_b32_e32 v14, 0xffff0000, v16
	v_lshlrev_b32_e32 v15, 16, v17
	v_and_b32_e32 v16, 0xffff0000, v17
	v_mul_f32_e32 v17, 0xbfb8aa3b, v13
	v_add_f32_e32 v9, 1.0, v9
	v_exp_f32_e32 v17, v17
	v_add_f32_e32 v12, 1.0, v12
	v_rcp_f32_e32 v9, v9
	v_mul_f32_e32 v5, v5, v10
	v_mul_f32_e32 v10, 0xbfb8aa3b, v14
	v_add_f32_e32 v11, 1.0, v11
	v_rcp_f32_e32 v12, v12
	v_exp_f32_e32 v10, v10
	v_rcp_f32_e32 v11, v11
	v_mul_f32_e32 v4, v4, v9
	v_add_f32_e32 v9, 1.0, v17
	v_mul_f32_e32 v7, v7, v12
	v_rcp_f32_e32 v9, v9
	v_add_f32_e32 v10, 1.0, v10
	v_mul_f32_e32 v12, 0xbfb8aa3b, v15
	v_mul_f32_e32 v6, v6, v11
	s_waitcnt lgkmcnt(0)
	v_mul_f32_e32 v11, v18, v13
	v_rcp_f32_e32 v10, v10
	v_exp_f32_e32 v12, v12
	v_mul_f32_e32 v13, 0xbfb8aa3b, v16
	v_exp_f32_e32 v13, v13
	v_mul_f32_e32 v9, v11, v9
	v_mul_f32_e32 v11, v19, v14
	v_mul_f32_e32 v10, v11, v10
	v_add_f32_e32 v11, 1.0, v12
	v_rcp_f32_e32 v11, v11
	v_add_f32_e32 v12, 1.0, v13
	v_rcp_f32_e32 v12, v12
	v_mul_f32_e32 v13, v20, v15
	v_mul_f32_e32 v11, v13, v11
	v_mul_f32_e32 v13, v21, v16
	v_mul_f32_e32 v12, v13, v12
	v_cvt_pk_bf16_f32 v4, v4, v5
	v_cvt_pk_bf16_f32 v5, v6, v7
	v_cvt_pk_bf16_f32 v6, v9, v10
	v_cvt_pk_bf16_f32 v7, v11, v12
	v_lshl_add_u64 v[10:11], v[2:3], 0, v[24:25]
	ds_read_b128 v[14:17], v8 offset:10240
	ds_read_b128 v[18:21], v8 offset:10256
	global_store_dwordx4 v[22:23], v[4:7], off
	v_add_u32_e32 v22, 0x6c000, v96
	v_mov_b32_e32 v23, v97
	v_lshl_add_u64 v[24:25], v[0:1], 0, v[24:25]
	v_add_u32_e32 v96, 0x7e000, v96
	v_lshl_add_u64 v[26:27], v[2:3], 0, v[96:97]
	s_waitcnt vmcnt(7)
; __device__ __forceinline__ unsigned cvt_pk_bf16(float lo, float hi) { unsigned r; asm volatile("v_cvt_pk_bf16_f32 %0, %1, %2" : "=v"(r) : "v"(lo), "v"(hi)); return r; }
; __device__ __forceinline__ float bf_lo(unsigned u) { return __uint_as_float(u << 16); }
; __device__ __forceinline__ float bf_hi(unsigned u) { return __uint_as_float(u & 0xffff0000u); }
; __device__ __forceinline__ float sigmoidf_(float x) { return __builtin_amdgcn_rcpf(1.f + __expf(-x)); }
; __device__ __forceinline__ void store_gated(const f32x16* v, float* stg, bf16_t* out, const bf16_t* gate, int lane, int r32, int hi, bool write) {
;     ...
;   for (int it = 0; it < 8; ++it) {
;     const int row = it * 4 + (lane >> 4), c8 = (lane & 15) * 8;
;     const f32x4 a = *(const f32x4*)(stg + row * 128 + c8), b = *(const f32x4*)(stg + row * 128 + c8 + 4);
;     const u32x4 g = *(const u32x4*)(gate + (long)row * INC + c8);
;     float z[8] = {bf_lo(g.x), bf_hi(g.x), bf_lo(g.y), bf_hi(g.y), bf_lo(g.z), bf_hi(g.z), bf_lo(g.w), bf_hi(g.w)};
;     float y[8];
; #pragma unroll
;     for (int e = 0; e < 8; ++e) y[e] = (e < 4 ? a[e] : b[e - 4]) * z[e] * sigmoidf_(z[e]);
;     u32x4 w; w.x = cvt_pk_bf16(y[0], y[1]); w.y = cvt_pk_bf16(y[2], y[3]); w.z = cvt_pk_bf16(y[4], y[5]); w.w = cvt_pk_bf16(y[6], y[7]);
;     if (write) *(u32x4*)(out + (long)row * INC + c8) = w; else if (y[0] == 123.456f) out[0] = 0;
	v_mov_b32_e32 v10, v136
	v_mov_b32_e32 v11, v137
	v_mov_b32_e32 v12, v138
	v_mov_b32_e32 v13, v139
	v_lshlrev_b32_e32 v4, 16, v10
	v_and_b32_e32 v5, 0xffff0000, v10
	v_lshlrev_b32_e32 v6, 16, v11
	v_and_b32_e32 v7, 0xffff0000, v11
	v_lshlrev_b32_e32 v9, 16, v12
	v_and_b32_e32 v10, 0xffff0000, v12
	v_lshlrev_b32_e32 v11, 16, v13
	v_and_b32_e32 v12, 0xffff0000, v13
	s_waitcnt lgkmcnt(1)
	v_mul_f32_e32 v13, v14, v4
	v_mul_f32_e32 v4, 0xbfb8aa3b, v4
	v_mul_f32_e32 v14, v15, v5
	v_mul_f32_e32 v5, 0xbfb8aa3b, v5
	v_mul_f32_e32 v15, v16, v6
	v_mul_f32_e32 v6, 0xbfb8aa3b, v6
	v_mul_f32_e32 v16, v17, v7
	v_mul_f32_e32 v7, 0xbfb8aa3b, v7
	s_waitcnt lgkmcnt(0)
	v_mul_f32_e32 v17, v18, v9
	v_mul_f32_e32 v18, v19, v10
	v_mul_f32_e32 v10, 0xbfb8aa3b, v10
	v_mul_f32_e32 v19, v20, v11
	v_mul_f32_e32 v11, 0xbfb8aa3b, v11
	v_mul_f32_e32 v9, 0xbfb8aa3b, v9
	v_mul_f32_e32 v20, v21, v12
	v_mul_f32_e32 v12, 0xbfb8aa3b, v12
	v_exp_f32_e32 v4, v4
	v_exp_f32_e32 v5, v5
	v_exp_f32_e32 v6, v6
	v_exp_f32_e32 v7, v7
	v_exp_f32_e32 v10, v10
	v_exp_f32_e32 v11, v11
	v_exp_f32_e32 v9, v9
	v_exp_f32_e32 v12, v12
	v_add_f32_e32 v4, 1.0, v4
	v_add_f32_e32 v5, 1.0, v5
	v_add_f32_e32 v6, 1.0, v6
	v_add_f32_e32 v7, 1.0, v7
	v_add_f32_e32 v10, 1.0, v10
	v_add_f32_e32 v11, 1.0, v11
	v_add_f32_e32 v9, 1.0, v9
	v_add_f32_e32 v12, 1.0, v12
	v_rcp_f32_e32 v4, v4
	v_rcp_f32_e32 v5, v5
	v_rcp_f32_e32 v6, v6
	v_rcp_f32_e32 v7, v7
	v_rcp_f32_e32 v10, v10
	v_rcp_f32_e32 v11, v11
	v_rcp_f32_e32 v9, v9
	v_rcp_f32_e32 v12, v12
	v_mul_f32_e32 v4, v13, v4
	v_mul_f32_e32 v5, v14, v5
	v_mul_f32_e32 v6, v15, v6
	v_mul_f32_e32 v7, v16, v7
	v_mul_f32_e32 v10, v18, v10
	v_mul_f32_e32 v11, v19, v11
	v_mul_f32_e32 v9, v17, v9
	v_mul_f32_e32 v12, v20, v12
	v_cvt_pk_bf16_f32 v4, v4, v5
	v_cvt_pk_bf16_f32 v5, v6, v7
	v_cvt_pk_bf16_f32 v6, v9, v10
	v_cvt_pk_bf16_f32 v7, v11, v12
	v_lshl_add_u64 v[10:11], v[2:3], 0, v[22:23]
	ds_read_b128 v[14:17], v8 offset:12288
	ds_read_b128 v[18:21], v8 offset:12304
	global_store_dwordx4 v[24:25], v[4:7], off
	s_waitcnt vmcnt(7)
	v_mov_b32_e32 v10, v140
	v_mov_b32_e32 v11, v141
	v_mov_b32_e32 v12, v142
	v_mov_b32_e32 v13, v143
	v_lshlrev_b32_e32 v2, 16, v10
	v_and_b32_e32 v3, 0xffff0000, v10
	v_lshlrev_b32_e32 v4, 16, v11
	v_and_b32_e32 v5, 0xffff0000, v11
	v_lshlrev_b32_e32 v6, 16, v12
	v_and_b32_e32 v10, 0xffff0000, v13
	v_and_b32_e32 v7, 0xffff0000, v12
	v_lshlrev_b32_e32 v9, 16, v13
	s_waitcnt lgkmcnt(1)
	v_mul_f32_e32 v11, v14, v2
	v_mul_f32_e32 v2, 0xbfb8aa3b, v2
	v_mul_f32_e32 v12, v15, v3
	v_mul_f32_e32 v3, 0xbfb8aa3b, v3
	v_mul_f32_e32 v13, v16, v4
	v_mul_f32_e32 v4, 0xbfb8aa3b, v4
	v_mul_f32_e32 v14, v17, v5
	v_mul_f32_e32 v5, 0xbfb8aa3b, v5
	s_waitcnt lgkmcnt(0)
	v_mul_f32_e32 v15, v18, v6
	v_mul_f32_e32 v18, v21, v10
	v_mul_f32_e32 v10, 0xbfb8aa3b, v10
	v_mul_f32_e32 v6, 0xbfb8aa3b, v6
	v_mul_f32_e32 v16, v19, v7
	v_mul_f32_e32 v7, 0xbfb8aa3b, v7
	v_mul_f32_e32 v17, v20, v9
	v_mul_f32_e32 v9, 0xbfb8aa3b, v9
	v_exp_f32_e32 v2, v2
	v_exp_f32_e32 v3, v3
	v_exp_f32_e32 v4, v4
	v_exp_f32_e32 v5, v5
	v_exp_f32_e32 v10, v10
	v_exp_f32_e32 v6, v6
	v_exp_f32_e32 v7, v7
	v_exp_f32_e32 v9, v9
	v_add_f32_e32 v2, 1.0, v2
	v_add_f32_e32 v3, 1.0, v3
	v_add_f32_e32 v4, 1.0, v4
	v_add_f32_e32 v5, 1.0, v5
	v_add_f32_e32 v10, 1.0, v10
	v_add_f32_e32 v6, 1.0, v6
	v_add_f32_e32 v7, 1.0, v7
	v_add_f32_e32 v9, 1.0, v9
	v_rcp_f32_e32 v2, v2
	v_rcp_f32_e32 v3, v3
	v_rcp_f32_e32 v4, v4
	v_rcp_f32_e32 v5, v5
	v_rcp_f32_e32 v10, v10
	v_rcp_f32_e32 v6, v6
	v_rcp_f32_e32 v7, v7
	v_rcp_f32_e32 v9, v9
	v_mul_f32_e32 v2, v11, v2
	v_mul_f32_e32 v3, v12, v3
	v_mul_f32_e32 v4, v13, v4
	v_mul_f32_e32 v5, v14, v5
	v_mul_f32_e32 v10, v18, v10
	v_mul_f32_e32 v6, v15, v6
	v_mul_f32_e32 v7, v16, v7
	v_mul_f32_e32 v9, v17, v9
	v_cvt_pk_bf16_f32 v2, v2, v3
	v_cvt_pk_bf16_f32 v3, v4, v5
	v_cvt_pk_bf16_f32 v4, v6, v7
	v_cvt_pk_bf16_f32 v5, v9, v10
	ds_read_b128 v[14:17], v8 offset:14336
	ds_read_b128 v[6:9], v8 offset:14352
	v_lshl_add_u64 v[18:19], v[0:1], 0, v[22:23]
	v_lshl_add_u64 v[20:21], v[0:1], 0, v[96:97]
	global_store_dwordx4 v[18:19], v[2:5], off
	s_waitcnt vmcnt(7)
	v_mov_b32_e32 v10, v186
	v_mov_b32_e32 v11, v187
	v_mov_b32_e32 v12, v188
	v_mov_b32_e32 v13, v189
	v_lshlrev_b32_e32 v0, 16, v13
	v_lshlrev_b32_e32 v1, 16, v10
	v_and_b32_e32 v2, 0xffff0000, v10
	v_lshlrev_b32_e32 v3, 16, v11
	v_and_b32_e32 v4, 0xffff0000, v11
	v_lshlrev_b32_e32 v5, 16, v12
	v_and_b32_e32 v10, 0xffff0000, v12
	v_and_b32_e32 v11, 0xffff0000, v13
	v_mul_f32_e32 v12, 0xbfb8aa3b, v0
	v_mul_f32_e32 v13, 0xbfb8aa3b, v3
	s_waitcnt lgkmcnt(1)
	v_mul_f32_e32 v3, v16, v3
	v_mul_f32_e32 v16, 0xbfb8aa3b, v2
	v_mul_f32_e32 v2, v15, v2
	v_mul_f32_e32 v15, 0xbfb8aa3b, v1
	s_waitcnt lgkmcnt(0)
	v_mul_f32_e32 v0, v8, v0
	v_mul_f32_e32 v8, 0xbfb8aa3b, v10
	v_mul_f32_e32 v7, v7, v10
	v_mul_f32_e32 v10, 0xbfb8aa3b, v5
	v_mul_f32_e32 v5, v6, v5
	v_mul_f32_e32 v6, 0xbfb8aa3b, v4
	v_mul_f32_e32 v1, v14, v1
	v_mul_f32_e32 v9, v9, v11
	v_mul_f32_e32 v11, 0xbfb8aa3b, v11
	v_exp_f32_e32 v12, v12
	v_exp_f32_e32 v13, v13
	v_exp_f32_e32 v14, v16
	v_exp_f32_e32 v15, v15
	v_exp_f32_e32 v8, v8
	v_exp_f32_e32 v10, v10
	v_exp_f32_e32 v6, v6
	v_exp_f32_e32 v11, v11
	v_add_f32_e32 v12, 1.0, v12
	v_add_f32_e32 v13, 1.0, v13
	v_add_f32_e32 v14, 1.0, v14
	v_add_f32_e32 v15, 1.0, v15
	v_add_f32_e32 v8, 1.0, v8
	v_add_f32_e32 v10, 1.0, v10
	v_add_f32_e32 v6, 1.0, v6
	v_add_f32_e32 v11, 1.0, v11
	v_rcp_f32_e32 v12, v12
	v_rcp_f32_e32 v13, v13
	v_rcp_f32_e32 v14, v14
	v_rcp_f32_e32 v15, v15
	v_rcp_f32_e32 v8, v8
	v_rcp_f32_e32 v10, v10
	v_rcp_f32_e32 v6, v6
	v_rcp_f32_e32 v11, v11
	v_mul_f32_e32 v4, v17, v4
	v_mul_f32_e32 v12, v0, v12
	v_mul_f32_e32 v3, v3, v13
	v_mul_f32_e32 v0, v2, v14
	v_mul_f32_e32 v1, v1, v15
	v_mul_f32_e32 v7, v7, v8
	v_mul_f32_e32 v5, v5, v10
	v_mul_f32_e32 v4, v4, v6
	v_mul_f32_e32 v6, v9, v11
	v_cvt_pk_bf16_f32 v0, v1, v0
	v_cvt_pk_bf16_f32 v1, v3, v4
	v_cvt_pk_bf16_f32 v2, v5, v7
	v_cvt_pk_bf16_f32 v3, v12, v6
	global_store_dwordx4 v[20:21], v[0:3], off
	s_barrier
